# E42: prompt-FoX K/V prefetch distance 2 tiles (two landing sets by tile parity); LDS stage-in of tile t+1 moved from the end of the tile to right after the QK MFMAs for computing waves; on E41
# baseline (speedup 1.0000x reference)
.LBB0_1387:
	s_or_b64 exec, exec, s[18:19]
	s_movk_i32 s15, 0x90
	v_mul_lo_u32 v147, v4, s15
	v_lshlrev_b32_e32 v153, 4, v8
	v_add3_u32 v8, 0, v147, v153
	s_waitcnt lgkmcnt(0)
	s_barrier
	s_barrier
	ds_write_b128 v8, v[130:133]
	v_mad_u64_u32 v[8:9], s[16:17], v4, 48, v[8:9]
	v_mul_lo_u32 v174, v6, s15
	v_lshlrev_b32_e32 v175, 4, v5
	ds_write_b128 v8, v[134:137] offset:18432
	v_add3_u32 v8, 0, v174, v175
	v_lshrrev_b32_e32 v2, 2, v2
	s_cmp_lt_i32 s13, s12
	s_movk_i32 s18, 0xc0
	ds_write_b128 v8, v[138:141]
	v_mad_u64_u32 v[8:9], s[16:17], v6, 48, v[8:9]
	v_and_or_b32 v5, v2, 3, v216
	v_and_or_b32 v2, v2, 4, v225
	v_mov_b32_e32 v16, v3
	v_mov_b32_e32 v17, v3
	s_cselect_b64 s[84:85], -1, 0
	s_add_i32 s14, s9, 0x7f
	s_add_i32 s13, s13, s8
	v_mul_lo_u32 v173, v4, s18
	v_mul_lo_u32 v191, v6, s18
	ds_write_b128 v8, v[142:145] offset:18432
	v_lshlrev_b32_e32 v193, 3, v2
	v_mul_u32_u24_e32 v194, 0xc0, v5
	v_add_u32_e32 v196, 0x80, v6
	v_add_u32_e32 v197, 0x80, v4
	v_mov_b32_e32 v2, v3
	v_mov_b32_e32 v4, v3
	v_mov_b32_e32 v5, v3
	v_mov_b32_e32 v6, v3
	v_mov_b32_e32 v7, v3
	v_mov_b32_e32 v8, v3
	v_mov_b32_e32 v9, v3
	v_mov_b32_e32 v10, v3
	v_mov_b32_e32 v11, v3
	v_mov_b32_e32 v12, v3
	v_mov_b32_e32 v13, v3
	v_mov_b32_e32 v14, v3
	v_mov_b32_e32 v15, v3
	v_mov_b64_e32 v[32:33], v[16:17]
	v_mov_b64_e32 v[48:49], v[16:17]
	s_lshr_b32 s14, s14, 7
	s_movk_i32 s72, 0x90
	s_movk_i32 s73, 0xc0
	s_add_i32 s15, s13, 31
	v_add_u32_e32 v195, s13, v188
	s_mov_b32 s16, 0
	v_mov_b32_e32 v158, 0xf149f2ca
	v_mov_b32_e32 v192, 0
	v_mov_b32_e32 v198, v187
	v_mov_b64_e32 v[30:31], v[14:15]
	v_mov_b64_e32 v[28:29], v[12:13]
	v_mov_b64_e32 v[26:27], v[10:11]
	v_mov_b64_e32 v[24:25], v[8:9]
	v_mov_b64_e32 v[22:23], v[6:7]
	v_mov_b64_e32 v[20:21], v[4:5]
	v_mov_b64_e32 v[18:19], v[2:3]
	v_mov_b64_e32 v[46:47], v[14:15]
	v_mov_b64_e32 v[44:45], v[12:13]
	v_mov_b64_e32 v[42:43], v[10:11]
	v_mov_b64_e32 v[40:41], v[8:9]
	v_mov_b64_e32 v[38:39], v[6:7]
	v_mov_b64_e32 v[36:37], v[4:5]
	v_mov_b64_e32 v[34:35], v[2:3]
	s_mov_b32 s18, 0
	s_waitcnt lgkmcnt(0)
	s_barrier
	v_add_u32_e32 v4, 0, v197
	v_ashrrev_i32_e32 v5, 31, v4
	v_lshlrev_b64 v[4:5], 9, v[4:5]
	v_lshl_add_u64 v[4:5], v[4:5], 0, v[148:149]
	v_lshlrev_b64 v[4:5], 1, v[4:5]
	v_lshl_add_u64 v[6:7], s[64:65], 0, v[4:5]
	v_lshl_add_u64 v[4:5], s[66:67], 0, v[4:5]
	v_add_u32_e32 v250, 0, v196
	v_ashrrev_i32_e32 v251, 31, v250
	v_lshlrev_b64 v[250:251], 9, v[250:251]
	v_lshl_add_u64 v[250:251], v[250:251], 0, v[156:157]
	v_lshlrev_b64 v[250:251], 1, v[250:251]
	v_lshl_add_u64 v[252:253], s[66:67], 0, v[250:251]
	v_lshl_add_u64 v[250:251], s[64:65], 0, v[250:251]
	global_load_dwordx4 v[204:207], v[4:5], off
	global_load_dwordx4 v[200:203], v[6:7], off
	global_load_dwordx4 v[208:211], v[250:251], off
	global_load_dwordx4 v[246:249], v[252:253], off
.LBB0_1388:
	s_add_i32 s17, s18, 1
	s_cmp_lt_u32 s17, s14
	s_cselect_b64 s[90:91], -1, 0
	s_add_i32 s99, s18, 2
	s_cmp_ge_u32 s99, s14
	s_cbranch_scc1 .LBB0_1390
	s_add_i32 s99, s16, 0x80
	v_add_u32_e32 v4, s99, v197
	v_ashrrev_i32_e32 v5, 31, v4
	v_lshlrev_b64 v[4:5], 9, v[4:5]
	v_lshl_add_u64 v[4:5], v[4:5], 0, v[148:149]
	v_lshlrev_b64 v[4:5], 1, v[4:5]
	v_lshl_add_u64 v[6:7], s[64:65], 0, v[4:5]
	v_lshl_add_u64 v[4:5], s[66:67], 0, v[4:5]
	v_add_u32_e32 v250, s99, v196
	v_ashrrev_i32_e32 v251, 31, v250
	v_lshlrev_b64 v[250:251], 9, v[250:251]
	v_lshl_add_u64 v[250:251], v[250:251], 0, v[156:157]
	v_lshlrev_b64 v[250:251], 1, v[250:251]
	v_lshl_add_u64 v[252:253], s[66:67], 0, v[250:251]
	v_lshl_add_u64 v[250:251], s[64:65], 0, v[250:251]
	s_bitcmp1_b32 s18, 0
	s_cbranch_scc1 .Lfxd_gB
	global_load_dwordx4 v[134:137], v[4:5], off
	global_load_dwordx4 v[130:133], v[6:7], off
	global_load_dwordx4 v[138:141], v[250:251], off
	global_load_dwordx4 v[142:145], v[252:253], off
	s_branch .LBB0_1390
.Lfxd_gB:
	global_load_dwordx4 v[204:207], v[4:5], off
	global_load_dwordx4 v[200:203], v[6:7], off
	global_load_dwordx4 v[208:211], v[250:251], off
	global_load_dwordx4 v[246:249], v[252:253], off
.LBB0_1390:
	s_cmp_le_i32 s16, s15
	s_cselect_b64 s[20:21], -1, 0
	s_and_b64 s[20:21], s[84:85], s[20:21]
	s_andn2_b64 vcc, exec, s[20:21]
	s_cbranch_vccnz .LBB0_1396
	s_bitcmp1_b32 s18, 0
	s_cselect_b32 s18, 0xa800, 0
	s_add_i32 s70, s18, 0
	ds_read_b128 v[82:85], v198
	ds_read_b128 v[86:89], v198 offset:32
	ds_read_b128 v[90:93], v198 offset:64
	ds_read_b128 v[94:97], v198 offset:96
	v_add3_u32 v2, s70, v214, v186
	ds_read_b128 v[226:229], v2
	ds_read_b128 v[230:233], v2 offset:32
	ds_read_b128 v[234:237], v2 offset:64
	ds_read_b128 v[238:241], v2 offset:96
	ds_read_b128 v[50:53], v198 offset:128
	ds_read_b128 v[54:57], v198 offset:160
	ds_read_b128 v[58:61], v198 offset:192
	ds_read_b128 v[62:65], v198 offset:224
	s_add_i32 s18, s16, 0x7f
	s_cmp_le_i32 s18, s13
	s_waitcnt lgkmcnt(7)
	v_mfma_f32_32x32x16_bf16 v[82:97], v[226:229], v[114:117], v[82:97]
	ds_read_b128 v[4:7], v2 offset:4608
	s_waitcnt lgkmcnt(7)
	v_mfma_f32_32x32x16_bf16 v[82:97], v[230:233], v[118:121], v[82:97]
	ds_read_b128 v[8:11], v2 offset:4640
	s_waitcnt lgkmcnt(7)
	v_mfma_f32_32x32x16_bf16 v[82:97], v[234:237], v[122:125], v[82:97]
	ds_read_b128 v[12:15], v2 offset:4672
	s_waitcnt lgkmcnt(7)
	v_mfma_f32_32x32x16_bf16 v[82:97], v[238:241], v[126:129], v[82:97]
	ds_read_b128 v[160:163], v2 offset:4704
	ds_read_b128 v[66:69], v198 offset:256
	ds_read_b128 v[70:73], v198 offset:288
	ds_read_b128 v[74:77], v198 offset:320
	ds_read_b128 v[78:81], v198 offset:352
	s_waitcnt lgkmcnt(7)
	v_mfma_f32_32x32x16_bf16 v[50:65], v[4:7], v[114:117], v[50:65]
	ds_read_b128 v[226:229], v2 offset:9216
	s_waitcnt lgkmcnt(7)
	v_mfma_f32_32x32x16_bf16 v[50:65], v[8:11], v[118:121], v[50:65]
	ds_read_b128 v[230:233], v2 offset:9248
	s_waitcnt lgkmcnt(7)
	v_mfma_f32_32x32x16_bf16 v[50:65], v[12:15], v[122:125], v[50:65]
	ds_read_b128 v[234:237], v2 offset:9280
	s_waitcnt lgkmcnt(7)
	v_mfma_f32_32x32x16_bf16 v[50:65], v[160:163], v[126:129], v[50:65]
	ds_read_b128 v[238:241], v2 offset:9312
	ds_read_b128 v[98:101], v198 offset:384
	ds_read_b128 v[102:105], v198 offset:416
	ds_read_b128 v[106:109], v198 offset:448
	ds_read_b128 v[110:113], v198 offset:480
	s_waitcnt lgkmcnt(7)
	v_mfma_f32_32x32x16_bf16 v[66:81], v[226:229], v[114:117], v[66:81]
	ds_read_b128 v[4:7], v2 offset:13824
	s_waitcnt lgkmcnt(7)
	v_mfma_f32_32x32x16_bf16 v[66:81], v[230:233], v[118:121], v[66:81]
	ds_read_b128 v[8:11], v2 offset:13856
	s_waitcnt lgkmcnt(7)
	v_mfma_f32_32x32x16_bf16 v[66:81], v[234:237], v[122:125], v[66:81]
	ds_read_b128 v[12:15], v2 offset:13888
	s_waitcnt lgkmcnt(7)
	v_mfma_f32_32x32x16_bf16 v[66:81], v[238:241], v[126:129], v[66:81]
	ds_read_b128 v[160:163], v2 offset:13920
	s_waitcnt lgkmcnt(3)
	v_mfma_f32_32x32x16_bf16 v[98:113], v[4:7], v[114:117], v[98:113]
	s_waitcnt lgkmcnt(2)
	v_mfma_f32_32x32x16_bf16 v[98:113], v[8:11], v[118:121], v[98:113]
	s_waitcnt lgkmcnt(1)
	v_mfma_f32_32x32x16_bf16 v[98:113], v[12:15], v[122:125], v[98:113]
	s_waitcnt lgkmcnt(0)
	v_mfma_f32_32x32x16_bf16 v[98:113], v[160:163], v[126:129], v[98:113]
	s_cselect_b32 s99, 1, 0
	s_cmp_eq_u64 s[90:91], 0
	s_cbranch_scc1 .Lfxd_nolw
	s_bitcmp1_b32 s17, 0
	s_cselect_b32 s100, 0xa800, 0
	v_add3_u32 v250, s100, v147, v153
	v_add3_u32 v251, s100, v173, v153
	v_add3_u32 v252, s100, v174, v175
	v_add3_u32 v253, s100, v191, v175
	s_add_i32 s101, s17, 1
	s_cmp_lt_u32 s101, s14
	s_cbranch_scc1 .Lfxd_w4m
	s_waitcnt vmcnt(0)
	s_branch .Lfxd_wdm

.Lfxd_wdm:
	s_bitcmp1_b32 s17, 0
	s_cbranch_scc1 .Lfxd_lwBm
	ds_write_b128 v250, v[130:133]
	ds_write_b128 v251, v[134:137] offset:18432
	ds_write_b128 v252, v[138:141]
	ds_write_b128 v253, v[142:145] offset:18432
	s_branch .Lfxd_nolw
.Lfxd_lwBm:
	ds_write_b128 v250, v[200:203]
	ds_write_b128 v251, v[204:207] offset:18432
	ds_write_b128 v252, v[208:211]
	ds_write_b128 v253, v[246:249] offset:18432
.Lfxd_nolw:
	s_cmp_lg_u32 s99, 0
	s_cbranch_scc1 .LBB0_1393
	v_cmp_gt_i32_e64 s[46:47], 26, v195
	v_cmp_gt_i32_e64 s[48:49], 27, v195
	v_cmp_gt_i32_e64 s[44:45], 25, v195
	s_and_b64 s[46:47], s[48:49], s[46:47]
	v_cmp_gt_i32_e64 s[42:43], 24, v195
	v_cndmask_b32_e64 v97, v97, v190, s[48:49]
	v_cndmask_b32_e64 v96, v96, v190, s[46:47]
	s_and_b64 s[44:45], s[46:47], s[44:45]
	v_cmp_gt_i32_e64 s[46:47], 58, v195
	v_cmp_gt_i32_e64 s[48:49], 59, v195
	v_cmp_gt_i32_e64 s[40:41], 19, v195
	v_cndmask_b32_e64 v95, v95, v190, s[44:45]
	s_and_b64 s[42:43], s[44:45], s[42:43]
	v_cmp_gt_i32_e64 s[44:45], 57, v195
	s_and_b64 s[46:47], s[48:49], s[46:47]
	v_cmp_gt_i32_e64 s[38:39], 18, v195
	v_cndmask_b32_e64 v94, v94, v190, s[42:43]
	s_and_b64 s[40:41], s[42:43], s[40:41]
	v_cmp_gt_i32_e64 s[42:43], 56, v195
	v_cndmask_b32_e64 v65, v65, v190, s[48:49]
	v_cndmask_b32_e64 v64, v64, v190, s[46:47]
	s_and_b64 s[44:45], s[46:47], s[44:45]
	s_movk_i32 s46, 0x5a
	s_movk_i32 s48, 0x5b
	v_cmp_gt_i32_e64 s[36:37], 17, v195
	v_cndmask_b32_e64 v93, v93, v190, s[40:41]
	s_and_b64 s[38:39], s[40:41], s[38:39]
	v_cmp_gt_i32_e64 s[40:41], 51, v195
	v_cndmask_b32_e64 v63, v63, v190, s[44:45]
	s_and_b64 s[42:43], s[44:45], s[42:43]
	s_movk_i32 s44, 0x59
	v_cmp_gt_i32_e64 s[46:47], s46, v195
	v_cmp_gt_i32_e64 s[48:49], s48, v195
	v_cmp_gt_i32_e64 s[34:35], 16, v195
	v_cndmask_b32_e64 v92, v92, v190, s[38:39]
	s_and_b64 s[36:37], s[38:39], s[36:37]
	v_cmp_gt_i32_e64 s[38:39], 50, v195
	v_cndmask_b32_e64 v62, v62, v190, s[42:43]
	s_and_b64 s[40:41], s[42:43], s[40:41]
	s_movk_i32 s42, 0x58
	v_cmp_gt_i32_e64 s[44:45], s44, v195
	s_and_b64 s[46:47], s[48:49], s[46:47]
	v_cmp_gt_i32_e64 s[30:31], 11, v195
	v_cndmask_b32_e64 v91, v91, v190, s[36:37]
	s_and_b64 s[34:35], s[36:37], s[34:35]
	v_cmp_gt_i32_e64 s[36:37], 49, v195
	v_cndmask_b32_e64 v61, v61, v190, s[40:41]
	s_and_b64 s[38:39], s[40:41], s[38:39]
	s_movk_i32 s40, 0x53
	v_cmp_gt_i32_e64 s[42:43], s42, v195
	s_and_b64 s[44:45], s[46:47], s[44:45]
	v_cmp_gt_i32_e64 s[28:29], 10, v195
	v_cndmask_b32_e64 v90, v90, v190, s[34:35]
	s_and_b64 s[30:31], s[34:35], s[30:31]
	v_cmp_gt_i32_e64 s[34:35], 48, v195
	v_cndmask_b32_e64 v60, v60, v190, s[38:39]
	s_and_b64 s[36:37], s[38:39], s[36:37]
	s_movk_i32 s38, 0x52
	v_cmp_gt_i32_e64 s[40:41], s40, v195
	v_cndmask_b32_e64 v81, v81, v190, s[48:49]
	v_cndmask_b32_e64 v80, v80, v190, s[46:47]
	s_and_b64 s[42:43], s[44:45], s[42:43]
	s_movk_i32 s46, 0x7a
	s_movk_i32 s48, 0x7b
	v_cmp_gt_i32_e64 s[26:27], 9, v195
	v_cndmask_b32_e64 v89, v89, v190, s[30:31]
	s_and_b64 s[28:29], s[30:31], s[28:29]
	v_cmp_gt_i32_e64 s[30:31], 43, v195
	v_cndmask_b32_e64 v59, v59, v190, s[36:37]
	s_and_b64 s[34:35], s[36:37], s[34:35]
	s_movk_i32 s36, 0x51
	v_cmp_gt_i32_e64 s[38:39], s38, v195
	v_cndmask_b32_e64 v79, v79, v190, s[44:45]
	s_and_b64 s[40:41], s[42:43], s[40:41]
	s_movk_i32 s44, 0x79
	v_cmp_gt_i32_e64 s[46:47], s46, v195
	v_cmp_gt_i32_e64 s[48:49], s48, v195
	v_cmp_gt_i32_e64 s[24:25], 8, v195
	v_cndmask_b32_e64 v88, v88, v190, s[28:29]
	s_and_b64 s[26:27], s[28:29], s[26:27]
	v_cmp_gt_i32_e64 s[28:29], 42, v195
	v_cndmask_b32_e64 v58, v58, v190, s[34:35]
	s_and_b64 s[30:31], s[34:35], s[30:31]
	s_movk_i32 s34, 0x50
	v_cmp_gt_i32_e64 s[36:37], s36, v195
	v_cndmask_b32_e64 v78, v78, v190, s[42:43]
	s_and_b64 s[38:39], s[40:41], s[38:39]
	s_movk_i32 s42, 0x78
	v_cmp_gt_i32_e64 s[44:45], s44, v195
	s_and_b64 s[46:47], s[48:49], s[46:47]
	v_cmp_gt_i32_e64 s[22:23], 3, v195
	v_cndmask_b32_e64 v87, v87, v190, s[26:27]
	s_and_b64 s[24:25], s[26:27], s[24:25]
	v_cmp_gt_i32_e64 s[26:27], 41, v195
	v_cndmask_b32_e64 v57, v57, v190, s[30:31]
	s_and_b64 s[28:29], s[30:31], s[28:29]
	s_movk_i32 s30, 0x4b
	v_cmp_gt_i32_e64 s[34:35], s34, v195
	v_cndmask_b32_e64 v77, v77, v190, s[40:41]
	s_and_b64 s[36:37], s[38:39], s[36:37]
	s_movk_i32 s40, 0x73
	v_cmp_gt_i32_e64 s[42:43], s42, v195
	s_and_b64 s[44:45], s[46:47], s[44:45]
	v_cmp_gt_i32_e64 s[20:21], 2, v195
	v_cndmask_b32_e64 v86, v86, v190, s[24:25]
	s_and_b64 s[22:23], s[24:25], s[22:23]
	v_cmp_gt_i32_e64 s[24:25], 40, v195
	v_cndmask_b32_e64 v56, v56, v190, s[28:29]
	s_and_b64 s[26:27], s[28:29], s[26:27]
	s_movk_i32 s28, 0x4a
	v_cmp_gt_i32_e64 s[30:31], s30, v195
	v_cndmask_b32_e64 v76, v76, v190, s[38:39]
	s_and_b64 s[34:35], s[36:37], s[34:35]
	s_movk_i32 s38, 0x72
	v_cmp_gt_i32_e64 s[40:41], s40, v195
	s_and_b64 s[42:43], s[44:45], s[42:43]
	v_cmp_gt_i32_e64 s[18:19], 1, v195
	v_cndmask_b32_e64 v85, v85, v190, s[22:23]
	s_and_b64 s[20:21], s[22:23], s[20:21]
	v_cmp_gt_i32_e64 s[22:23], 35, v195
	v_cndmask_b32_e64 v55, v55, v190, s[26:27]
	s_and_b64 s[24:25], s[26:27], s[24:25]
	s_movk_i32 s26, 0x49
	v_cmp_gt_i32_e64 s[28:29], s28, v195
	v_cndmask_b32_e64 v75, v75, v190, s[36:37]
	s_and_b64 s[30:31], s[34:35], s[30:31]
	s_movk_i32 s36, 0x71
	v_cmp_gt_i32_e64 s[38:39], s38, v195
	s_and_b64 s[40:41], s[42:43], s[40:41]
	v_cmp_gt_i32_e32 vcc, 0, v195
	v_cndmask_b32_e64 v84, v84, v190, s[20:21]
	s_and_b64 s[18:19], s[20:21], s[18:19]
	v_cmp_gt_i32_e64 s[20:21], 34, v195
	v_cndmask_b32_e64 v54, v54, v190, s[24:25]
	s_and_b64 s[22:23], s[24:25], s[22:23]
	s_movk_i32 s24, 0x48
	v_cmp_gt_i32_e64 s[26:27], s26, v195
	v_cndmask_b32_e64 v74, v74, v190, s[34:35]
	s_and_b64 s[28:29], s[30:31], s[28:29]
	s_movk_i32 s34, 0x70
	v_cmp_gt_i32_e64 s[36:37], s36, v195
	s_and_b64 s[38:39], s[40:41], s[38:39]
	v_cndmask_b32_e64 v83, v83, v190, s[18:19]
	s_and_b64 vcc, s[18:19], vcc
	v_cmp_gt_i32_e64 s[18:19], 33, v195
	v_cndmask_b32_e64 v53, v53, v190, s[22:23]
	s_and_b64 s[20:21], s[22:23], s[20:21]
	s_movk_i32 s22, 0x43
	v_cmp_gt_i32_e64 s[24:25], s24, v195
	v_cndmask_b32_e64 v73, v73, v190, s[30:31]
	s_and_b64 s[26:27], s[28:29], s[26:27]
	s_movk_i32 s30, 0x6b
	v_cmp_gt_i32_e64 s[34:35], s34, v195
	s_and_b64 s[36:37], s[38:39], s[36:37]
	v_cndmask_b32_e32 v82, v82, v190, vcc
	v_cmp_gt_i32_e32 vcc, 32, v195
	v_cndmask_b32_e64 v52, v52, v190, s[20:21]
	s_and_b64 s[18:19], s[20:21], s[18:19]
	s_movk_i32 s20, 0x42
	v_cmp_gt_i32_e64 s[22:23], s22, v195
	v_cndmask_b32_e64 v72, v72, v190, s[28:29]
	s_and_b64 s[24:25], s[26:27], s[24:25]
	s_movk_i32 s28, 0x6a
	v_cmp_gt_i32_e64 s[30:31], s30, v195
	s_and_b64 s[34:35], s[36:37], s[34:35]
	v_cndmask_b32_e64 v51, v51, v190, s[18:19]
	s_and_b64 vcc, s[18:19], vcc
	s_movk_i32 s18, 0x41
	v_cmp_gt_i32_e64 s[20:21], s20, v195
	v_cndmask_b32_e64 v71, v71, v190, s[26:27]
	s_and_b64 s[22:23], s[24:25], s[22:23]
	s_movk_i32 s26, 0x69
	v_cmp_gt_i32_e64 s[28:29], s28, v195
	s_and_b64 s[30:31], s[34:35], s[30:31]
	v_cmp_gt_i32_e64 s[18:19], s18, v195
	v_cndmask_b32_e64 v70, v70, v190, s[24:25]
	s_and_b64 s[20:21], s[22:23], s[20:21]
	s_movk_i32 s24, 0x68
	v_cmp_gt_i32_e64 s[26:27], s26, v195
	s_and_b64 s[28:29], s[30:31], s[28:29]
	v_cndmask_b32_e32 v50, v50, v190, vcc
	v_cmp_gt_i32_e32 vcc, 64, v195
	v_cndmask_b32_e64 v69, v69, v190, s[22:23]
	s_and_b64 s[18:19], s[20:21], s[18:19]
	s_movk_i32 s22, 0x63
	v_cmp_gt_i32_e64 s[24:25], s24, v195
	s_and_b64 s[26:27], s[28:29], s[26:27]
	v_cndmask_b32_e64 v68, v68, v190, s[20:21]
	v_cndmask_b32_e64 v67, v67, v190, s[18:19]
	s_and_b64 vcc, s[18:19], vcc
	s_movk_i32 s18, 0x60
	s_movk_i32 s20, 0x62
	v_cmp_gt_i32_e64 s[22:23], s22, v195
	s_and_b64 s[24:25], s[26:27], s[24:25]
	v_cndmask_b32_e32 v66, v66, v190, vcc
	v_cmp_gt_i32_e32 vcc, s18, v195
	s_movk_i32 s18, 0x61
	v_cmp_gt_i32_e64 s[20:21], s20, v195
	s_and_b64 s[22:23], s[24:25], s[22:23]
	v_cmp_gt_i32_e64 s[18:19], s18, v195
	s_and_b64 s[20:21], s[22:23], s[20:21]
	s_and_b64 s[18:19], s[20:21], s[18:19]
	s_and_b64 vcc, s[18:19], vcc
	v_cndmask_b32_e64 v113, v113, v190, s[48:49]
	v_cndmask_b32_e64 v112, v112, v190, s[46:47]
	v_cndmask_b32_e64 v111, v111, v190, s[44:45]
	v_cndmask_b32_e64 v110, v110, v190, s[42:43]
	v_cndmask_b32_e64 v109, v109, v190, s[40:41]
	v_cndmask_b32_e64 v108, v108, v190, s[38:39]
	v_cndmask_b32_e64 v107, v107, v190, s[36:37]
	v_cndmask_b32_e64 v106, v106, v190, s[34:35]
	v_cndmask_b32_e64 v105, v105, v190, s[30:31]
	v_cndmask_b32_e64 v104, v104, v190, s[28:29]
	v_cndmask_b32_e64 v103, v103, v190, s[26:27]
	v_cndmask_b32_e64 v102, v102, v190, s[24:25]
	v_cndmask_b32_e64 v101, v101, v190, s[22:23]
	v_cndmask_b32_e64 v100, v100, v190, s[20:21]
	v_cndmask_b32_e64 v99, v99, v190, s[18:19]
	v_cndmask_b32_e32 v98, v98, v190, vcc

.LBB0_1395:
	v_pk_add_f32 v[10:11], v[86:87], v[158:159] op_sel_hi:[1,0] neg_lo:[0,1] neg_hi:[0,1]
	v_pk_add_f32 v[4:5], v[82:83], v[158:159] op_sel_hi:[1,0] neg_lo:[0,1] neg_hi:[0,1]
	v_exp_f32_e32 v168, v10
	v_exp_f32_e32 v169, v11
	v_pk_add_f32 v[10:11], v[88:89], v[158:159] op_sel_hi:[1,0] neg_lo:[0,1] neg_hi:[0,1]
	v_pk_add_f32 v[6:7], v[84:85], v[158:159] op_sel_hi:[1,0] neg_lo:[0,1] neg_hi:[0,1]
	v_exp_f32_e32 v170, v10
	v_exp_f32_e32 v171, v11
	v_pk_add_f32 v[10:11], v[90:91], v[158:159] op_sel_hi:[1,0] neg_lo:[0,1] neg_hi:[0,1]
	v_exp_f32_e32 v4, v4
	v_exp_f32_e32 v160, v10
	v_exp_f32_e32 v161, v11
	v_pk_add_f32 v[10:11], v[92:93], v[158:159] op_sel_hi:[1,0] neg_lo:[0,1] neg_hi:[0,1]
	v_exp_f32_e32 v5, v5
	v_exp_f32_e32 v162, v10
	v_exp_f32_e32 v163, v11
	v_pk_add_f32 v[10:11], v[94:95], v[158:159] op_sel_hi:[1,0] neg_lo:[0,1] neg_hi:[0,1]
	v_add3_u32 v2, s70, v193, v194
	v_exp_f32_e32 v164, v10
	v_exp_f32_e32 v165, v11
	v_pk_add_f32 v[10:11], v[96:97], v[158:159] op_sel_hi:[1,0] neg_lo:[0,1] neg_hi:[0,1]
	v_exp_f32_e32 v6, v6
	v_exp_f32_e32 v166, v10
	v_exp_f32_e32 v167, v11
	v_pk_add_f32 v[10:11], v[50:51], v[158:159] op_sel_hi:[1,0] neg_lo:[0,1] neg_hi:[0,1]
	v_exp_f32_e32 v7, v7
	v_exp_f32_e32 v90, v10
	v_exp_f32_e32 v91, v11
	v_pk_add_f32 v[10:11], v[52:53], v[158:159] op_sel_hi:[1,0] neg_lo:[0,1] neg_hi:[0,1]
	v_pk_add_f32 v[8:9], v[4:5], 0 op_sel_hi:[1,0]
	v_exp_f32_e32 v92, v10
	v_exp_f32_e32 v93, v11
	v_pk_add_f32 v[10:11], v[54:55], v[158:159] op_sel_hi:[1,0] neg_lo:[0,1] neg_hi:[0,1]
	v_pk_add_f32 v[8:9], v[6:7], v[8:9]
	v_exp_f32_e32 v94, v10
	v_exp_f32_e32 v95, v11
	v_pk_add_f32 v[10:11], v[56:57], v[158:159] op_sel_hi:[1,0] neg_lo:[0,1] neg_hi:[0,1]
	v_cvt_pk_bf16_f32 v4, v4, v5
	v_exp_f32_e32 v96, v10
	v_exp_f32_e32 v97, v11
	v_pk_add_f32 v[10:11], v[58:59], v[158:159] op_sel_hi:[1,0] neg_lo:[0,1] neg_hi:[0,1]
	v_cvt_pk_bf16_f32 v5, v6, v7
	v_exp_f32_e32 v82, v10
	v_exp_f32_e32 v83, v11
	v_pk_add_f32 v[10:11], v[60:61], v[158:159] op_sel_hi:[1,0] neg_lo:[0,1] neg_hi:[0,1]
	v_cvt_pk_bf16_f32 v6, v168, v169
	v_exp_f32_e32 v84, v10
	v_exp_f32_e32 v85, v11
	v_pk_add_f32 v[10:11], v[62:63], v[158:159] op_sel_hi:[1,0] neg_lo:[0,1] neg_hi:[0,1]
	v_cvt_pk_bf16_f32 v7, v170, v171
	v_exp_f32_e32 v86, v10
	v_exp_f32_e32 v87, v11
	v_pk_add_f32 v[10:11], v[64:65], v[158:159] op_sel_hi:[1,0] neg_lo:[0,1] neg_hi:[0,1]
	v_pk_add_f32 v[8:9], v[168:169], v[8:9]
	v_exp_f32_e32 v88, v10
	v_exp_f32_e32 v89, v11
	v_pk_add_f32 v[10:11], v[66:67], v[158:159] op_sel_hi:[1,0] neg_lo:[0,1] neg_hi:[0,1]
	v_pk_add_f32 v[8:9], v[170:171], v[8:9]
	v_exp_f32_e32 v66, v10
	v_exp_f32_e32 v67, v11
	v_pk_add_f32 v[10:11], v[68:69], v[158:159] op_sel_hi:[1,0] neg_lo:[0,1] neg_hi:[0,1]
	v_pk_add_f32 v[8:9], v[160:161], v[8:9]
	v_exp_f32_e32 v68, v10
	v_exp_f32_e32 v69, v11
	v_pk_add_f32 v[10:11], v[70:71], v[158:159] op_sel_hi:[1,0] neg_lo:[0,1] neg_hi:[0,1]
	v_pk_add_f32 v[8:9], v[162:163], v[8:9]
	v_exp_f32_e32 v70, v10
	v_exp_f32_e32 v71, v11
	v_pk_add_f32 v[10:11], v[72:73], v[158:159] op_sel_hi:[1,0] neg_lo:[0,1] neg_hi:[0,1]
	v_pk_add_f32 v[8:9], v[164:165], v[8:9]
	v_exp_f32_e32 v72, v10
	v_exp_f32_e32 v73, v11
	v_pk_add_f32 v[10:11], v[74:75], v[158:159] op_sel_hi:[1,0] neg_lo:[0,1] neg_hi:[0,1]
	v_pk_add_f32 v[8:9], v[166:167], v[8:9]
	v_exp_f32_e32 v58, v10
	v_exp_f32_e32 v59, v11
	v_pk_add_f32 v[10:11], v[76:77], v[158:159] op_sel_hi:[1,0] neg_lo:[0,1] neg_hi:[0,1]
	ds_read_b64_tr_b16 v[74:75], v2 offset:18432
	ds_read_b64_tr_b16 v[76:77], v2 offset:19968
	s_waitcnt lgkmcnt(0)
	v_mfma_f32_32x32x16_bf16 v[34:49], v[74:77], v[4:7], v[34:49]
	ds_read_b64_tr_b16 v[74:75], v2 offset:18496
	ds_read_b64_tr_b16 v[76:77], v2 offset:20032
	v_add_f32_e64 v8, v90, v8
	v_add_f32_e64 v9, v91, v9
	v_exp_f32_e32 v60, v10
	v_pk_add_f32 v[8:9], v[92:93], v[8:9]
	v_exp_f32_e32 v61, v11
	v_pk_add_f32 v[8:9], v[94:95], v[8:9]
	v_pk_add_f32 v[10:11], v[78:79], v[158:159] op_sel_hi:[1,0] neg_lo:[0,1] neg_hi:[0,1]
	s_waitcnt lgkmcnt(0)
	v_mfma_f32_32x32x16_bf16 v[18:33], v[74:77], v[4:7], v[18:33]
	ds_read_b64_tr_b16 v[74:75], v2 offset:21504
	ds_read_b64_tr_b16 v[76:77], v2 offset:23040
	v_cvt_pk_bf16_f32 v4, v160, v161
	v_cvt_pk_bf16_f32 v5, v162, v163
	v_cvt_pk_bf16_f32 v6, v164, v165
	v_cvt_pk_bf16_f32 v7, v166, v167
	v_pk_add_f32 v[8:9], v[96:97], v[8:9]
	v_exp_f32_e32 v62, v10
	s_waitcnt lgkmcnt(0)
	v_mfma_f32_32x32x16_bf16 v[34:49], v[74:77], v[4:7], v[34:49]
	ds_read_b64_tr_b16 v[74:75], v2 offset:21568
	ds_read_b64_tr_b16 v[76:77], v2 offset:23104
	v_add_f32_e64 v8, v82, v8
	v_add_f32_e64 v9, v83, v9
	v_exp_f32_e32 v63, v11
	v_pk_add_f32 v[8:9], v[84:85], v[8:9]
	v_pk_add_f32 v[10:11], v[80:81], v[158:159] op_sel_hi:[1,0] neg_lo:[0,1] neg_hi:[0,1]
	v_pk_add_f32 v[8:9], v[86:87], v[8:9]
	v_exp_f32_e32 v64, v10
	s_waitcnt lgkmcnt(0)
	v_mfma_f32_32x32x16_bf16 v[18:33], v[74:77], v[4:7], v[18:33]
	ds_read_b64_tr_b16 v[74:75], v2 offset:24576
	ds_read_b64_tr_b16 v[76:77], v2 offset:26112
	v_cvt_pk_bf16_f32 v4, v90, v91
	v_cvt_pk_bf16_f32 v5, v92, v93
	v_cvt_pk_bf16_f32 v6, v94, v95
	v_cvt_pk_bf16_f32 v7, v96, v97
	v_pk_add_f32 v[8:9], v[88:89], v[8:9]
	v_exp_f32_e32 v65, v11
	s_waitcnt lgkmcnt(0)
	v_mfma_f32_32x32x16_bf16 v[34:49], v[74:77], v[4:7], v[34:49]
	ds_read_b64_tr_b16 v[74:75], v2 offset:24640
	ds_read_b64_tr_b16 v[76:77], v2 offset:26176
	v_add_f32_e64 v8, v66, v8
	v_add_f32_e64 v9, v67, v9
	v_add_f32_e64 v10, v98, -v158
	v_add_f32_e64 v11, v99, -v158
	v_pk_add_f32 v[8:9], v[68:69], v[8:9]
	v_exp_f32_e32 v50, v10
	v_pk_add_f32 v[8:9], v[70:71], v[8:9]
	v_exp_f32_e32 v51, v11
	s_waitcnt lgkmcnt(0)
	v_mfma_f32_32x32x16_bf16 v[18:33], v[74:77], v[4:7], v[18:33]
	ds_read_b64_tr_b16 v[74:75], v2 offset:27648
	ds_read_b64_tr_b16 v[76:77], v2 offset:29184
	v_cvt_pk_bf16_f32 v4, v82, v83
	v_cvt_pk_bf16_f32 v5, v84, v85
	v_cvt_pk_bf16_f32 v6, v86, v87
	v_cvt_pk_bf16_f32 v7, v88, v89
	v_pk_add_f32 v[8:9], v[72:73], v[8:9]
	v_pk_add_f32 v[10:11], v[100:101], v[158:159] op_sel_hi:[1,0] neg_lo:[0,1] neg_hi:[0,1]
	s_waitcnt lgkmcnt(0)
	v_mfma_f32_32x32x16_bf16 v[34:49], v[74:77], v[4:7], v[34:49]
	ds_read_b64_tr_b16 v[74:75], v2 offset:27712
	ds_read_b64_tr_b16 v[76:77], v2 offset:29248
	v_add_f32_e64 v8, v58, v8
	v_add_f32_e64 v9, v59, v9
	v_exp_f32_e32 v52, v10
	v_pk_add_f32 v[8:9], v[60:61], v[8:9]
	v_exp_f32_e32 v53, v11
	v_pk_add_f32 v[8:9], v[62:63], v[8:9]
	v_pk_add_f32 v[10:11], v[102:103], v[158:159] op_sel_hi:[1,0] neg_lo:[0,1] neg_hi:[0,1]
	s_waitcnt lgkmcnt(0)
	v_mfma_f32_32x32x16_bf16 v[18:33], v[74:77], v[4:7], v[18:33]
	v_cvt_pk_bf16_f32 v4, v66, v67
	v_cvt_pk_bf16_f32 v5, v68, v69
	ds_read_b64_tr_b16 v[66:67], v2 offset:30720
	ds_read_b64_tr_b16 v[68:69], v2 offset:32256
	v_cvt_pk_bf16_f32 v6, v70, v71
	v_cvt_pk_bf16_f32 v7, v72, v73
	v_pk_add_f32 v[8:9], v[64:65], v[8:9]
	v_exp_f32_e32 v54, v10
	s_waitcnt lgkmcnt(0)
	v_mfma_f32_32x32x16_bf16 v[34:49], v[66:69], v[4:7], v[34:49]
	ds_read_b64_tr_b16 v[66:67], v2 offset:30784
	ds_read_b64_tr_b16 v[68:69], v2 offset:32320
	v_add_f32_e64 v8, v50, v8
	v_add_f32_e64 v9, v51, v9
	v_exp_f32_e32 v55, v11
	v_pk_add_f32 v[10:11], v[104:105], v[158:159] op_sel_hi:[1,0] neg_lo:[0,1] neg_hi:[0,1]
	v_pk_add_f32 v[8:9], v[52:53], v[8:9]
	v_exp_f32_e32 v56, v10
	v_exp_f32_e32 v57, v11
	s_waitcnt lgkmcnt(0)
	v_mfma_f32_32x32x16_bf16 v[18:33], v[66:69], v[4:7], v[18:33]
	v_cvt_pk_bf16_f32 v4, v58, v59
	v_cvt_pk_bf16_f32 v5, v60, v61
	ds_read_b64_tr_b16 v[58:59], v2 offset:33792
	ds_read_b64_tr_b16 v[60:61], v2 offset:35328
	v_cvt_pk_bf16_f32 v6, v62, v63
	v_cvt_pk_bf16_f32 v7, v64, v65
	v_pk_add_f32 v[10:11], v[106:107], v[158:159] op_sel_hi:[1,0] neg_lo:[0,1] neg_hi:[0,1]
	v_pk_add_f32 v[12:13], v[108:109], v[158:159] op_sel_hi:[1,0] neg_lo:[0,1] neg_hi:[0,1]
	s_waitcnt lgkmcnt(0)
	v_mfma_f32_32x32x16_bf16 v[34:49], v[58:61], v[4:7], v[34:49]
	ds_read_b64_tr_b16 v[58:59], v2 offset:33856
	ds_read_b64_tr_b16 v[60:61], v2 offset:35392
	v_exp_f32_e32 v10, v10
	v_exp_f32_e32 v11, v11
	v_exp_f32_e32 v12, v12
	v_exp_f32_e32 v13, v13
	v_pk_add_f32 v[8:9], v[54:55], v[8:9]
	v_pk_add_f32 v[14:15], v[110:111], v[158:159] op_sel_hi:[1,0] neg_lo:[0,1] neg_hi:[0,1]
	s_waitcnt lgkmcnt(0)
	v_mfma_f32_32x32x16_bf16 v[18:33], v[58:61], v[4:7], v[18:33]
	v_cvt_pk_bf16_f32 v4, v50, v51
	v_cvt_pk_bf16_f32 v5, v52, v53
	ds_read_b64_tr_b16 v[50:51], v2 offset:36864
	ds_read_b64_tr_b16 v[52:53], v2 offset:38400
	v_cvt_pk_bf16_f32 v6, v54, v55
	v_cvt_pk_bf16_f32 v7, v56, v57
	v_pk_add_f32 v[8:9], v[56:57], v[8:9]
	v_pk_add_f32 v[16:17], v[112:113], v[158:159] op_sel_hi:[1,0] neg_lo:[0,1] neg_hi:[0,1]
	s_waitcnt lgkmcnt(0)
	v_mfma_f32_32x32x16_bf16 v[34:49], v[50:53], v[4:7], v[34:49]
	ds_read_b64_tr_b16 v[50:51], v2 offset:36928
	ds_read_b64_tr_b16 v[52:53], v2 offset:38464
	v_add_f32_e64 v8, v10, v8
	v_add_f32_e64 v9, v11, v9
	v_exp_f32_e32 v14, v14
	v_pk_add_f32 v[8:9], v[12:13], v[8:9]
	v_exp_f32_e32 v15, v15
	v_exp_f32_e32 v16, v16
	v_exp_f32_e32 v17, v17
	s_waitcnt lgkmcnt(0)
	v_mfma_f32_32x32x16_bf16 v[18:33], v[50:53], v[4:7], v[18:33]
	v_cvt_pk_bf16_f32 v4, v10, v11
	v_cvt_pk_bf16_f32 v5, v12, v13
	ds_read_b64_tr_b16 v[10:11], v2 offset:39936
	ds_read_b64_tr_b16 v[12:13], v2 offset:41472
	v_cvt_pk_bf16_f32 v6, v14, v15
	v_cvt_pk_bf16_f32 v7, v16, v17
	v_pk_add_f32 v[8:9], v[14:15], v[8:9]
	s_waitcnt lgkmcnt(0)
	v_mfma_f32_32x32x16_bf16 v[34:49], v[10:13], v[4:7], v[34:49]
	ds_read_b64_tr_b16 v[10:11], v2 offset:40000
	ds_read_b64_tr_b16 v[12:13], v2 offset:41536
	v_add_f32_e64 v8, v16, v8
	v_add_f32_e64 v9, v17, v9
	v_add_f32_e32 v2, v8, v9
	v_add_f32_e32 v192, v192, v2
	s_waitcnt lgkmcnt(0)
	v_mfma_f32_32x32x16_bf16 v[18:33], v[10:13], v[4:7], v[18:33]
	s_branch .LBB0_1398
.LBB0_1396:
	s_andn2_b64 vcc, exec, s[90:91]
	s_cbranch_vccnz .LBB0_1398
	s_bitcmp1_b32 s17, 0
	s_cselect_b32 s18, 0xa800, 0
	s_add_i32 s18, s18, 0
	v_add3_u32 v6, s18, v147, v153
	v_add3_u32 v2, s18, v191, v175
	v_add3_u32 v4, s18, v174, v175
	v_add3_u32 v5, s18, v173, v153
	s_add_i32 s101, s17, 1
	s_cmp_lt_u32 s101, s14
	s_cbranch_scc1 .Lfxd_w4s
	s_waitcnt vmcnt(0)
	s_branch .Lfxd_wds

.Lfxd_wds:
	s_bitcmp1_b32 s17, 0
	s_cbranch_scc1 .Lfxd_lwBs
	ds_write_b128 v6, v[130:133]
	ds_write_b128 v5, v[134:137] offset:18432
	ds_write_b128 v4, v[138:141]
	ds_write_b128 v2, v[142:145] offset:18432
	s_branch .LBB0_1398
.Lfxd_lwBs:
	ds_write_b128 v6, v[200:203]
	ds_write_b128 v5, v[204:207] offset:18432
	ds_write_b128 v4, v[208:211]
	ds_write_b128 v2, v[246:249] offset:18432
